# tabB_lat hand loop reads periodic rows once (rows multiple of 8/16/32), weight-transpose items 6 per round on blocks >=336
# speedup vs baseline: 1.1313x; 1.0023x over previous
.Ltb_loop:
	s_lshr_b32 s1, s0, 1
	s_and_b32 s2, s0, 1
	s_lshl_b32 s3, s2, 2
	s_lshl_b32 s6, s2, 31
	s_lshl_b32 s7, s0, 12
	s_add_u32 s8, s4, s7
	s_addc_u32 s9, s5, 0
	s_and_b32 s10, s1, 7
	s_cmp_lg_u32 s10, 0
	s_cbranch_scc1 .Ltb_n8
	s_and_b32 s10, s1, 15
	s_cmp_lg_u32 s10, 0
	s_cbranch_scc1 .Ltb_n4
	s_and_b32 s10, s1, 31
	s_cmp_lg_u32 s10, 0
	s_cbranch_scc1 .Ltb_n2
	v_mul_u32_u24_e32 v218, s1, v202
	v_and_b32_e32 v218, 0x7ff, v218
	v_lshl_add_u32 v218, v218, 3, s3
	ds_read_b32 v226, v218
	s_waitcnt lgkmcnt(0)
	v_xor_b32_e32 v226, s6, v226
	s_nop 1
	v_mov_b32_dpp v234, v226 quad_perm:[1,0,3,2] row_mask:0xf bank_mask:0xf
	v_cvt_pk_bf16_f32 v226, v226, v234
	s_mov_b32 exec_lo, 0x55555555
	s_mov_b32 exec_hi, 0x55555555
	global_store_dword v210, v226, s[8:9]
	global_store_dword v211, v226, s[8:9]
	global_store_dword v212, v226, s[8:9]
	global_store_dword v213, v226, s[8:9]
	global_store_dword v214, v226, s[8:9]
	global_store_dword v215, v226, s[8:9]
	global_store_dword v216, v226, s[8:9]
	global_store_dword v217, v226, s[8:9]
	s_mov_b64 exec, -1
	s_branch .Ltb_next
.Ltb_n2:
	v_mul_u32_u24_e32 v218, s1, v202
	v_and_b32_e32 v218, 0x7ff, v218
	v_lshl_add_u32 v218, v218, 3, s3
	ds_read_b32 v226, v218
	v_mul_u32_u24_e32 v219, s1, v203
	v_and_b32_e32 v219, 0x7ff, v219
	v_lshl_add_u32 v219, v219, 3, s3
	ds_read_b32 v227, v219
	s_waitcnt lgkmcnt(0)
	v_xor_b32_e32 v226, s6, v226
	v_xor_b32_e32 v227, s6, v227
	s_nop 1
	v_mov_b32_dpp v234, v226 quad_perm:[1,0,3,2] row_mask:0xf bank_mask:0xf
	v_mov_b32_dpp v235, v227 quad_perm:[1,0,3,2] row_mask:0xf bank_mask:0xf
	v_cvt_pk_bf16_f32 v226, v226, v234
	v_cvt_pk_bf16_f32 v227, v227, v235
	s_mov_b32 exec_lo, 0x55555555
	s_mov_b32 exec_hi, 0x55555555
	global_store_dword v210, v226, s[8:9]
	global_store_dword v211, v227, s[8:9]
	global_store_dword v212, v226, s[8:9]
	global_store_dword v213, v227, s[8:9]
	global_store_dword v214, v226, s[8:9]
	global_store_dword v215, v227, s[8:9]
	global_store_dword v216, v226, s[8:9]
	global_store_dword v217, v227, s[8:9]
	s_mov_b64 exec, -1
	s_branch .Ltb_next
.Ltb_n4:
	v_mul_u32_u24_e32 v218, s1, v202
	v_and_b32_e32 v218, 0x7ff, v218
	v_lshl_add_u32 v218, v218, 3, s3
	ds_read_b32 v226, v218
	v_mul_u32_u24_e32 v219, s1, v203
	v_and_b32_e32 v219, 0x7ff, v219
	v_lshl_add_u32 v219, v219, 3, s3
	ds_read_b32 v227, v219
	v_mul_u32_u24_e32 v220, s1, v204
	v_and_b32_e32 v220, 0x7ff, v220
	v_lshl_add_u32 v220, v220, 3, s3
	ds_read_b32 v228, v220
	v_mul_u32_u24_e32 v221, s1, v205
	v_and_b32_e32 v221, 0x7ff, v221
	v_lshl_add_u32 v221, v221, 3, s3
	ds_read_b32 v229, v221
	s_waitcnt lgkmcnt(0)
	v_xor_b32_e32 v226, s6, v226
	v_xor_b32_e32 v227, s6, v227
	v_xor_b32_e32 v228, s6, v228
	v_xor_b32_e32 v229, s6, v229
	s_nop 1
	v_mov_b32_dpp v234, v226 quad_perm:[1,0,3,2] row_mask:0xf bank_mask:0xf
	v_mov_b32_dpp v235, v227 quad_perm:[1,0,3,2] row_mask:0xf bank_mask:0xf
	v_mov_b32_dpp v236, v228 quad_perm:[1,0,3,2] row_mask:0xf bank_mask:0xf
	v_mov_b32_dpp v237, v229 quad_perm:[1,0,3,2] row_mask:0xf bank_mask:0xf
	v_cvt_pk_bf16_f32 v226, v226, v234
	v_cvt_pk_bf16_f32 v227, v227, v235
	v_cvt_pk_bf16_f32 v228, v228, v236
	v_cvt_pk_bf16_f32 v229, v229, v237
	s_mov_b32 exec_lo, 0x55555555
	s_mov_b32 exec_hi, 0x55555555
	global_store_dword v210, v226, s[8:9]
	global_store_dword v211, v227, s[8:9]
	global_store_dword v212, v228, s[8:9]
	global_store_dword v213, v229, s[8:9]
	global_store_dword v214, v226, s[8:9]
	global_store_dword v215, v227, s[8:9]
	global_store_dword v216, v228, s[8:9]
	global_store_dword v217, v229, s[8:9]
	s_mov_b64 exec, -1
	s_branch .Ltb_next
.Ltb_n8:
	v_mul_u32_u24_e32 v218, s1, v202
	v_and_b32_e32 v218, 0x7ff, v218
	v_lshl_add_u32 v218, v218, 3, s3
	ds_read_b32 v226, v218
	v_mul_u32_u24_e32 v219, s1, v203
	v_and_b32_e32 v219, 0x7ff, v219
	v_lshl_add_u32 v219, v219, 3, s3
	ds_read_b32 v227, v219
	v_mul_u32_u24_e32 v220, s1, v204
	v_and_b32_e32 v220, 0x7ff, v220
	v_lshl_add_u32 v220, v220, 3, s3
	ds_read_b32 v228, v220
	v_mul_u32_u24_e32 v221, s1, v205
	v_and_b32_e32 v221, 0x7ff, v221
	v_lshl_add_u32 v221, v221, 3, s3
	ds_read_b32 v229, v221
	v_mul_u32_u24_e32 v222, s1, v206
	v_and_b32_e32 v222, 0x7ff, v222
	v_lshl_add_u32 v222, v222, 3, s3
	ds_read_b32 v230, v222
	v_mul_u32_u24_e32 v223, s1, v207
	v_and_b32_e32 v223, 0x7ff, v223
	v_lshl_add_u32 v223, v223, 3, s3
	ds_read_b32 v231, v223
	v_mul_u32_u24_e32 v224, s1, v208
	v_and_b32_e32 v224, 0x7ff, v224
	v_lshl_add_u32 v224, v224, 3, s3
	ds_read_b32 v232, v224
	v_mul_u32_u24_e32 v225, s1, v209
	v_and_b32_e32 v225, 0x7ff, v225
	v_lshl_add_u32 v225, v225, 3, s3
	ds_read_b32 v233, v225
	s_waitcnt lgkmcnt(0)
	v_xor_b32_e32 v226, s6, v226
	v_xor_b32_e32 v227, s6, v227
	v_xor_b32_e32 v228, s6, v228
	v_xor_b32_e32 v229, s6, v229
	v_xor_b32_e32 v230, s6, v230
	v_xor_b32_e32 v231, s6, v231
	v_xor_b32_e32 v232, s6, v232
	v_xor_b32_e32 v233, s6, v233
	s_nop 1
	v_mov_b32_dpp v234, v226 quad_perm:[1,0,3,2] row_mask:0xf bank_mask:0xf
	v_mov_b32_dpp v235, v227 quad_perm:[1,0,3,2] row_mask:0xf bank_mask:0xf
	v_mov_b32_dpp v236, v228 quad_perm:[1,0,3,2] row_mask:0xf bank_mask:0xf
	v_mov_b32_dpp v237, v229 quad_perm:[1,0,3,2] row_mask:0xf bank_mask:0xf
	v_mov_b32_dpp v238, v230 quad_perm:[1,0,3,2] row_mask:0xf bank_mask:0xf
	v_mov_b32_dpp v239, v231 quad_perm:[1,0,3,2] row_mask:0xf bank_mask:0xf
	v_mov_b32_dpp v240, v232 quad_perm:[1,0,3,2] row_mask:0xf bank_mask:0xf
	v_mov_b32_dpp v241, v233 quad_perm:[1,0,3,2] row_mask:0xf bank_mask:0xf
	v_cvt_pk_bf16_f32 v226, v226, v234
	v_cvt_pk_bf16_f32 v227, v227, v235
	v_cvt_pk_bf16_f32 v228, v228, v236
	v_cvt_pk_bf16_f32 v229, v229, v237
	v_cvt_pk_bf16_f32 v230, v230, v238
	v_cvt_pk_bf16_f32 v231, v231, v239
	v_cvt_pk_bf16_f32 v232, v232, v240
	v_cvt_pk_bf16_f32 v233, v233, v241
	s_mov_b32 exec_lo, 0x55555555
	s_mov_b32 exec_hi, 0x55555555
	global_store_dword v210, v226, s[8:9]
	global_store_dword v211, v227, s[8:9]
	global_store_dword v212, v228, s[8:9]
	global_store_dword v213, v229, s[8:9]
	global_store_dword v214, v230, s[8:9]
	global_store_dword v215, v231, s[8:9]
	global_store_dword v216, v232, s[8:9]
	global_store_dword v217, v233, s[8:9]
	s_mov_b64 exec, -1
.Ltb_next:
	s_add_i32 s0, s0, 1
	s_and_b32 s1, s0, 7
	s_cmp_lg_u32 s1, 0
	s_cbranch_scc1 .Ltb_loop
	s_barrier
	v_and_b32_e32 v120, 63, v176
	v_lshrrev_b32_e32 v121, 6, v176
	v_lshlrev_b32_e32 v122, 2, v120
	v_mul_u32_u24_e32 v123, 65, v120
	v_add_lshl_u32 v123, v123, v121, 2
	v_lshrrev_b32_e32 v129, 2, v176
	v_mul_u32_u24_e32 v124, 65, v129
	v_lshlrev_b32_e32 v125, 11, v129
	v_and_b32_e32 v129, 3, v176
	v_lshl_add_u32 v124, v129, 4, v124
	v_lshlrev_b32_e32 v124, 2, v124
	v_lshl_add_u32 v125, v129, 5, v125
	v_add_u32_e32 v127, 0x4100, v123
	v_add_u32_e32 v128, 0x4100, v124
	s_mov_b32 s1, 0
	s_mov_b32 s0, s94
	s_cmpk_lt_u32 s94, 0x150
	s_cbranch_scc1 .Lwt_start
	s_sub_i32 s0, s94, 0x150
	s_mul_i32 s0, s0, 6
	s_addk_i32 s0, 0x150

.Lwt_loop:
	s_cmpk_lt_u32 s94, 0x150
	s_cbranch_scc1 .Lwt_adv_a0
	s_add_i32 s1, s1, 1
	s_cmp_lt_u32 s1, 6
	s_cbranch_scc0 .Lwt_adv_b0
	s_add_i32 s0, s0, 1
	s_branch .Lwt_adv_c0
.Lwt_adv_b0:
	s_mov_b32 s1, 0
	s_addk_i32 s0, 0x56b
	s_branch .Lwt_adv_c0
.Lwt_adv_a0:
	s_addk_i32 s0, 0x570

.Lwt_h0_go:
	v_cndmask_b32_e64 v130, 0, v130, s[22:23]
	v_cndmask_b32_e64 v131, 0, v131, s[22:23]
	v_cndmask_b32_e64 v132, 0, v132, s[22:23]
	v_cndmask_b32_e64 v133, 0, v133, s[22:23]
	v_cndmask_b32_e64 v134, 0, v134, s[22:23]
	v_cndmask_b32_e64 v135, 0, v135, s[22:23]
	v_cndmask_b32_e64 v136, 0, v136, s[22:23]
	v_cndmask_b32_e64 v137, 0, v137, s[22:23]
	v_cndmask_b32_e64 v138, 0, v138, s[22:23]
	v_cndmask_b32_e64 v139, 0, v139, s[22:23]
	v_cndmask_b32_e64 v140, 0, v140, s[22:23]
	v_cndmask_b32_e64 v141, 0, v141, s[22:23]
	v_cndmask_b32_e64 v142, 0, v142, s[22:23]
	v_cndmask_b32_e64 v143, 0, v143, s[22:23]
	v_cndmask_b32_e64 v144, 0, v144, s[22:23]
	v_cndmask_b32_e64 v145, 0, v145, s[22:23]
	ds_write2_b32 v123, v130, v131 offset0:0 offset1:4
	ds_write2_b32 v123, v132, v133 offset0:8 offset1:12
	ds_write2_b32 v123, v134, v135 offset0:16 offset1:20
	ds_write2_b32 v123, v136, v137 offset0:24 offset1:28
	ds_write2_b32 v123, v138, v139 offset0:32 offset1:36
	ds_write2_b32 v123, v140, v141 offset0:40 offset1:44
	ds_write2_b32 v123, v142, v143 offset0:48 offset1:52
	ds_write2_b32 v123, v144, v145 offset0:56 offset1:60
	s_waitcnt lgkmcnt(0)
	s_barrier
	ds_read2_b32 v[194:195], v124 offset0:0 offset1:1
	ds_read2_b32 v[196:197], v124 offset0:2 offset1:3
	ds_read2_b32 v[198:199], v124 offset0:4 offset1:5
	ds_read2_b32 v[200:201], v124 offset0:6 offset1:7
	ds_read2_b32 v[202:203], v124 offset0:8 offset1:9
	ds_read2_b32 v[204:205], v124 offset0:10 offset1:11
	ds_read2_b32 v[206:207], v124 offset0:12 offset1:13
	ds_read2_b32 v[208:209], v124 offset0:14 offset1:15
	s_waitcnt lgkmcnt(0)
	v_cvt_pk_bf16_f32 v194, v194, v195
	v_cvt_pk_bf16_f32 v195, v196, v197
	v_cvt_pk_bf16_f32 v196, v198, v199
	v_cvt_pk_bf16_f32 v197, v200, v201
	v_cvt_pk_bf16_f32 v198, v202, v203
	v_cvt_pk_bf16_f32 v199, v204, v205
	v_cvt_pk_bf16_f32 v200, v206, v207
	v_cvt_pk_bf16_f32 v201, v208, v209
	global_store_dwordx4 v125, v[194:197], s[12:13]
	global_store_dwordx4 v125, v[198:201], s[12:13] offset:16
	s_mov_b64 s[12:13], s[14:15]
	s_mov_b32 s19, 0
	s_cmpk_lt_u32 s0, 0x1040
	s_cbranch_scc0 .Lwt_done
	s_cmpk_lt_u32 s94, 0x150
	s_cbranch_scc1 .Lwt_adv_a1
	s_add_i32 s1, s1, 1
	s_cmp_lt_u32 s1, 6
	s_cbranch_scc0 .Lwt_adv_b1
	s_add_i32 s0, s0, 1
	s_branch .Lwt_adv_c1
